# FB: the two remaining in-loop grid barriers hand-written - static generation index, XCD leader bumps TOP without return and polls TOP itself (one round trip less), members poll XCD generation word
# baseline (speedup 1.0000x reference)
.LBB0_587:
	s_waitcnt vmcnt(0)
	s_barrier
	s_mov_b64 s[0:1], exec
	v_readlane_b32 s4, v234, 0
	v_readlane_b32 s5, v234, 1
	v_readlane_b32 s18, v232, 33
	s_and_b64 s[4:5], s[0:1], s[4:5]
	v_readlane_b32 s19, v232, 34
	s_mov_b64 exec, s[4:5]
	s_cbranch_execz .LBB0_635
	s_waitcnt vmcnt(0) expcnt(0) lgkmcnt(0)
	ds_read_b32 v3, v158
	ds_read_b32 v2, v159
	global_atomic_add v4, v[120:121], v160, off sc0
	s_lshl_b32 s9, s2, 1
	s_add_u32 s9, s9, 1
	s_waitcnt vmcnt(0) lgkmcnt(0)
	v_readfirstlane_b32 s6, v4
	v_readfirstlane_b32 s7, v3
	v_readfirstlane_b32 s8, v2
	s_nop 3
	s_add_u32 s10, s9, 1
	s_mul_i32 s11, s10, s7
	s_add_u32 s6, s6, 1
	s_cmp_eq_u32 s6, s11
	s_cbranch_scc1 .Lfbp_leader
	s_mov_b32 s4, 0
.Lfbp_mspin:
	s_sleep 1
	global_load_dword v4, v[122:123], off sc1
	s_waitcnt vmcnt(0)
	v_readfirstlane_b32 s6, v4
	s_nop 3
	s_cmp_lg_u32 s6, s9
	s_cbranch_scc1 .Lfbp_acq
	s_add_u32 s4, s4, 1
	s_cmp_lt_u32 s4, 0x8000
	s_cbranch_scc1 .Lfbp_mspin
	s_branch .Lfbp_acq
.Lfbp_leader:
	buffer_wbl2 sc1
	s_waitcnt vmcnt(0)
	v_readlane_b32 s4, v233, 60
	v_readlane_b32 s5, v233, 61
	s_mul_i32 s10, s10, s8
	s_nop 3
	global_atomic_add v1, v160, s[4:5]
	s_mov_b32 s11, 0
.Lfbp_lspin:
	global_load_dword v4, v1, s[4:5] sc1
	s_waitcnt vmcnt(0)
	v_readfirstlane_b32 s6, v4
	s_nop 3
	s_cmp_ge_u32 s6, s10
	s_cbranch_scc1 .Lfbp_rel
	s_sleep 1
	s_add_u32 s11, s11, 1
	s_cmp_lt_u32 s11, 0x8000
	s_cbranch_scc1 .Lfbp_lspin
.Lfbp_rel:
	s_waitcnt vmcnt(0)
	buffer_inv sc1
	global_atomic_add v[122:123], v160, off
	s_waitcnt vmcnt(0)
	s_branch .Lfbp_out

.Lfbp_out:
.LBB0_635:
	s_or_b64 exec, exec, s[0:1]
	s_lshl_b64 s[0:1], s[86:87], 2
	s_add_u32 s44, s80, s0
	s_addc_u32 s45, s81, s1
	s_lshl_b64 s[0:1], s[2:3], 2
	s_add_u32 s48, s80, s0
	s_addc_u32 s49, s81, s1
	s_lshl_b32 s86, s2, 6
	s_lshl_b64 s[56:57], s[2:3], 20
	s_lshl_b32 s26, s2, 8
	s_lshl_b64 s[74:75], s[2:3], 15
	v_readlane_b32 s4, v232, 6
	s_add_u32 s4, s4, s0
	v_readlane_b32 s0, v232, 7
	s_addc_u32 s5, s0, s1
	v_writelane_b32 v232, s4, 39
	s_lshl_b64 s[0:1], s[86:87], 2
	s_waitcnt lgkmcnt(0)
	v_writelane_b32 v232, s5, 40
	v_readlane_b32 s4, v234, 20
	v_readlane_b32 s14, v234, 30
	v_readlane_b32 s15, v234, 31
	s_add_u32 s92, s14, s0
	s_barrier
	s_addc_u32 s93, s15, s1
	v_readlane_b32 s0, v232, 8
	v_readlane_b32 s19, v234, 35
	s_add_u32 s27, s0, s56
	v_readlane_b32 s0, v232, 9
	s_addc_u32 s50, s0, s57
	s_mov_b64 s[84:85], 0
	s_movk_i32 s19, 0x70
	v_readlane_b32 s5, v234, 21
	v_readlane_b32 s6, v234, 22
	v_readlane_b32 s7, v234, 23
	v_readlane_b32 s8, v234, 24
	v_readlane_b32 s9, v234, 25
	v_readlane_b32 s10, v234, 26
	v_readlane_b32 s11, v234, 27
	v_readlane_b32 s12, v234, 28
	v_readlane_b32 s13, v234, 29
	v_readlane_b32 s16, v234, 32
	v_readlane_b32 s17, v234, 33
	v_readlane_b32 s18, v234, 34
	s_branch .LBB0_640

.LBB0_944:
	s_waitcnt vmcnt(0)
	s_barrier
	s_mov_b64 s[0:1], exec
	v_readlane_b32 s4, v234, 0
	v_readlane_b32 s5, v234, 1
	v_readlane_b32 s26, v232, 33
	v_readlane_b32 s38, v232, 35
	v_readlane_b32 s44, v232, 37
	v_readlane_b32 s12, v232, 29
	s_and_b64 s[4:5], s[0:1], s[4:5]
	v_readlane_b32 s27, v232, 34
	v_readlane_b32 s39, v232, 36
	v_readlane_b32 s45, v232, 38
	v_readlane_b32 s13, v232, 30
	s_mov_b64 exec, s[4:5]
	s_cbranch_execz .LBB0_992
	s_waitcnt vmcnt(0) expcnt(0) lgkmcnt(0)
	ds_read_b32 v3, v158
	ds_read_b32 v2, v159
	global_atomic_add v4, v[120:121], v160, off sc0
	s_lshl_b32 s9, s2, 1
	s_add_u32 s9, s9, 2
	s_waitcnt vmcnt(0) lgkmcnt(0)
	v_readfirstlane_b32 s6, v4
	v_readfirstlane_b32 s7, v3
	v_readfirstlane_b32 s8, v2
	s_nop 3
	s_add_u32 s10, s9, 1
	s_mul_i32 s11, s10, s7
	s_add_u32 s6, s6, 1
	s_cmp_eq_u32 s6, s11
	s_cbranch_scc1 .Lfbq_leader
	s_mov_b32 s4, 0

.Lfbq_out:
.LBB0_992:
	s_or_b64 exec, exec, s[0:1]
	v_mov_b32_e32 v6, v156
	s_waitcnt lgkmcnt(0)
	s_barrier
	s_lshl_b32 s0, s2, 21
	v_readlane_b32 s1, v232, 12
	s_add_u32 s12, s1, s0
	v_and_b32_e32 v0, 31, v6
	v_readlane_b32 s0, v232, 13
	v_lshlrev_b32_e32 v9, 2, v0
	v_ashrrev_i32_e32 v0, 1, v6
	s_addc_u32 s13, s0, 0
	v_readlane_b32 s0, v232, 16
	v_readlane_b32 s48, v234, 2
	v_and_b32_e32 v2, 0xffffffc0, v0
	v_readlane_b32 s1, v232, 17
	v_readlane_b32 s49, v234, 3
	v_ashrrev_i32_e32 v3, 31, v2
	v_lshlrev_b32_e32 v0, 2, v6
	s_and_b64 s[0:1], s[0:1], exec
	s_mov_b64 s[4:5], s[48:49]
	v_lshlrev_b32_e32 v7, 8, v6
	v_lshlrev_b64 v[66:67], 10, v[2:3]
	v_and_b32_e32 v2, 60, v0
	s_cselect_b32 s1, s5, s79
	s_cselect_b32 s0, s4, s78
	v_and_b32_e32 v8, 0xffffc000, v7
	v_lshlrev_b32_e32 v0, 2, v2
	v_lshl_add_u64 v[4:5], s[0:1], 0, v[0:1]
	v_or_b32_e32 v11, v8, v0
	v_lshlrev_b32_e32 v0, 5, v6
	v_bfe_u32 v3, v6, 4, 2
	v_and_b32_e32 v0, 0x400, v0
	v_or3_b32 v125, v8, v9, v0
	v_or_b32_e32 v0, 4, v3
	s_waitcnt vmcnt(1)
	v_lshlrev_b32_e32 v13, 8, v0
	v_lshlrev_b32_e32 v8, 10, v0
	v_or_b32_e32 v0, 8, v3
	v_lshlrev_b32_e32 v15, 8, v0
	v_lshlrev_b32_e32 v10, 10, v0
	v_or_b32_e32 v0, 12, v3
	v_lshlrev_b32_e32 v17, 8, v0
	v_lshlrev_b32_e32 v12, 10, v0
	v_or_b32_e32 v0, 16, v3
	v_lshlrev_b32_e32 v19, 8, v0
	v_lshlrev_b32_e32 v14, 10, v0
	v_or_b32_e32 v0, 20, v3
	v_lshlrev_b32_e32 v21, 8, v0
	v_lshlrev_b32_e32 v16, 10, v0
	v_or_b32_e32 v0, 24, v3
	v_lshlrev_b32_e32 v23, 8, v0
	v_lshlrev_b32_e32 v18, 10, v0
	v_or_b32_e32 v0, 28, v3
	v_lshlrev_b32_e32 v25, 8, v0
	v_lshlrev_b32_e32 v20, 10, v0
	v_or_b32_e32 v0, 32, v3
	v_lshlrev_b32_e32 v27, 8, v0
	v_lshlrev_b32_e32 v22, 10, v0
	v_or_b32_e32 v0, 36, v3
	v_lshlrev_b32_e32 v29, 8, v0
	v_lshlrev_b32_e32 v24, 10, v0
	v_or_b32_e32 v0, 40, v3
	v_lshlrev_b32_e32 v31, 8, v0
	v_lshlrev_b32_e32 v26, 10, v0
	v_or_b32_e32 v0, 44, v3
	v_lshlrev_b32_e32 v33, 8, v0
	v_lshlrev_b32_e32 v28, 10, v0
	v_or_b32_e32 v0, 48, v3
	v_lshlrev_b32_e32 v35, 8, v0
	v_lshlrev_b32_e32 v30, 10, v0
	v_or_b32_e32 v0, 52, v3
	v_lshlrev_b32_e32 v37, 8, v0
	v_lshlrev_b32_e32 v32, 10, v0
	v_or_b32_e32 v0, 56, v3
	v_readlane_b32 s54, v234, 8
	v_readlane_b32 s55, v234, 9
	v_readlane_b32 s56, v234, 10
	v_readlane_b32 s57, v234, 11
	v_readlane_b32 s58, v234, 12
	v_readlane_b32 s59, v234, 13
	v_readlane_b32 s62, v234, 16
	v_readlane_b32 s63, v234, 17
	v_lshlrev_b32_e32 v38, 8, v0
	v_lshlrev_b32_e32 v34, 10, v0
	v_or_b32_e32 v0, 60, v3
	v_readlane_b32 s50, v234, 4
	v_readlane_b32 s51, v234, 5
	v_readlane_b32 s52, v234, 6
	v_readlane_b32 s60, v234, 14
	v_readlane_b32 s61, v234, 15
	v_and_or_b32 v66, v6, 64, v66
	v_lshlrev_b32_e32 v9, 8, v3
	v_lshlrev_b32_e32 v6, 10, v3
	v_lshlrev_b32_e32 v3, 8, v0
	v_lshlrev_b32_e32 v36, 10, v0
	v_and_b32_e32 v0, 0x3000, v7
	v_readlane_b32 s48, v232, 18
	v_readlane_b32 s54, v232, 23
	v_readlane_b32 s58, v232, 25
	v_readlane_b32 s62, v232, 27
	v_readlane_b32 s56, v232, 29
	v_lshl_add_u64 v[68:69], v[4:5], 0, v[0:1]
	s_lshl_b64 s[0:1], s[2:3], 21
	s_mov_b32 s14, 0
	v_add_u32_e32 v144, v11, v9
	v_lshlrev_b32_e32 v70, 2, v6
	v_lshlrev_b32_e32 v72, 2, v2
	v_add_u32_e32 v145, v11, v13
	v_lshlrev_b32_e32 v74, 2, v8
	v_add_u32_e32 v146, v11, v15
	v_lshlrev_b32_e32 v76, 2, v10
	v_add_u32_e32 v147, v11, v17
	v_lshlrev_b32_e32 v78, 2, v12
	v_add_u32_e32 v148, v11, v19
	v_lshlrev_b32_e32 v80, 2, v14
	v_add_u32_e32 v149, v11, v21
	v_lshlrev_b32_e32 v82, 2, v16
	v_add_u32_e32 v150, v11, v23
	v_lshlrev_b32_e32 v84, 2, v18
	v_add_u32_e32 v151, v11, v25
	v_lshlrev_b32_e32 v86, 2, v20
	v_add_u32_e32 v152, v11, v27
	v_lshlrev_b32_e32 v88, 2, v22
	v_add_u32_e32 v153, v11, v29
	v_lshlrev_b32_e32 v90, 2, v24
	v_add_u32_e32 v154, v11, v31
	v_lshlrev_b32_e32 v92, 2, v26
	v_add_u32_e32 v155, v11, v33
	v_lshlrev_b32_e32 v94, 2, v28
	v_add_u32_e32 v180, v11, v35
	v_lshlrev_b32_e32 v96, 2, v30
	v_add_u32_e32 v181, v11, v37
	v_lshlrev_b32_e32 v98, 2, v32
	v_add_u32_e32 v182, v11, v38
	v_lshlrev_b32_e32 v100, 2, v34
	v_add_u32_e32 v183, v11, v3
	v_lshlrev_b32_e32 v102, 2, v36
	v_readlane_b32 s74, v234, 36
	v_readlane_b32 s60, v234, 38
	v_readlane_b32 s49, v232, 19
	v_readlane_b32 s50, v232, 20
	v_readlane_b32 s51, v232, 21
	v_readlane_b32 s52, v232, 22
	v_readlane_b32 s55, v232, 24
	v_readlane_b32 s59, v232, 26
	v_readlane_b32 s63, v232, 28
	v_readlane_b32 s57, v232, 30
	s_movk_i32 s3, 0x4000
	v_readlane_b32 s53, v234, 7
	v_readlane_b32 s75, v234, 37
	v_readlane_b32 s61, v234, 39
	s_branch .LBB0_995
